# LDS waits counted and moved to the first consumer of each pending read (in-order LDS completion), the original guarantee restored at every block end
# speedup vs baseline: 1.0022x; 1.0022x over previous
.LBB0_1086:
	s_waitcnt vmcnt(0)
	v_mul_f32_e32 v34, 0xbfb8aa3b, v33
	v_rndne_f32_e32 v35, v34
	v_sub_f32_e32 v36, v34, v35
	v_fma_f32 v34, v33, s85, -v34
	v_fmac_f32_e32 v34, 0xb2a5705f, v33
	v_add_f32_e32 v34, v36, v34
	v_exp_f32_e32 v34, v34
	v_cvt_i32_f32_e32 v35, v35
	v_cmp_nlt_f32_e32 vcc, s86, v33
	s_add_u32 s58, s42, 0x10000
	s_addc_u32 s59, s96, 0
	v_ldexp_f32 v34, v34, v35
	v_cndmask_b32_e32 v34, 0, v34, vcc
	v_cmp_ngt_f32_e32 vcc, s87, v33
	s_add_u32 s60, s97, 0x10000
	s_addc_u32 s61, s18, 0
	v_cndmask_b32_e32 v79, v224, v34, vcc
	v_add_f32_e32 v159, 1.0, v79
	v_frexp_mant_f32_e32 v33, v159
	v_cmp_gt_f32_e64 s[16:17], s89, v33
	v_mul_f32_e32 v33, 0xbfb8aa3b, v32
	v_rndne_f32_e32 v34, v33
	v_sub_f32_e32 v35, v33, v34
	v_fma_f32 v33, v32, s85, -v33
	v_fmac_f32_e32 v33, 0xb2a5705f, v32
	v_add_f32_e32 v33, v35, v33
	v_exp_f32_e32 v33, v33
	v_cvt_i32_f32_e32 v34, v34
	v_cmp_nlt_f32_e32 vcc, s86, v32
	s_mov_b32 m0, s21
	v_cmp_neq_f32_e64 s[10:11], s88, v79
	v_ldexp_f32 v33, v33, v34
	v_cndmask_b32_e32 v33, 0, v33, vcc
	v_cmp_ngt_f32_e32 vcc, s87, v32
	v_cmp_lt_f32_e64 s[12:13], |v79|, s91
	s_nop 0
	v_cndmask_b32_e32 v78, v224, v33, vcc
	v_add_f32_e32 v162, 1.0, v78
	v_frexp_mant_f32_e32 v32, v162
	v_cmp_gt_f32_e64 s[14:15], s89, v32
	ds_read_b128 v[32:35], v213
	ds_read_b128 v[36:39], v213 offset:34816
	ds_read_b128 v[40:43], v213 offset:64
	ds_read_b128 v[44:47], v213 offset:34880
	s_waitcnt lgkmcnt(0)
	v_mfma_f32_16x16x32_bf16 v[32:35], v[32:35], v[0:3], 0
	v_cmp_neq_f32_e64 s[6:7], s88, v78
	v_cmp_lt_f32_e64 s[8:9], |v78|, s91
	s_and_b64 vcc, exec, s[4:5]
	v_mfma_f32_16x16x32_bf16 v[36:39], v[36:39], v[0:3], 0
	v_mfma_f32_16x16x32_bf16 v[32:35], v[40:43], v[4:7], v[32:35]
	v_mfma_f32_16x16x32_bf16 v[36:39], v[44:47], v[4:7], v[36:39]
	ds_read_b128 v[40:43], v213 offset:128
	ds_read_b128 v[44:47], v213 offset:34944
	s_waitcnt lgkmcnt(1)
	v_mfma_f32_16x16x32_bf16 v[32:35], v[40:43], v[8:11], v[32:35]
	s_waitcnt lgkmcnt(0)
	v_mfma_f32_16x16x32_bf16 v[36:39], v[44:47], v[8:11], v[36:39]
	ds_read_b128 v[40:43], v213 offset:192
	ds_read_b128 v[44:47], v213 offset:35008
	s_waitcnt lgkmcnt(1)
	v_mfma_f32_16x16x32_bf16 v[32:35], v[40:43], v[12:15], v[32:35]
	s_waitcnt lgkmcnt(0)
	v_mfma_f32_16x16x32_bf16 v[36:39], v[44:47], v[12:15], v[36:39]
	ds_read_b128 v[40:43], v213 offset:256
	ds_read_b128 v[44:47], v213 offset:35072
	s_waitcnt lgkmcnt(1)
	v_mfma_f32_16x16x32_bf16 v[32:35], v[40:43], v[16:19], v[32:35]
	s_waitcnt lgkmcnt(0)
	v_mfma_f32_16x16x32_bf16 v[36:39], v[44:47], v[16:19], v[36:39]
	ds_read_b128 v[40:43], v213 offset:320
	ds_read_b128 v[44:47], v213 offset:35136
	s_waitcnt lgkmcnt(1)
	v_mfma_f32_16x16x32_bf16 v[32:35], v[40:43], v[20:23], v[32:35]
	s_waitcnt lgkmcnt(0)
	v_mfma_f32_16x16x32_bf16 v[36:39], v[44:47], v[20:23], v[36:39]
	ds_read_b128 v[40:43], v213 offset:384
	ds_read_b128 v[44:47], v213 offset:35200
	s_waitcnt lgkmcnt(1)
	v_mfma_f32_16x16x32_bf16 v[32:35], v[40:43], v[24:27], v[32:35]
	s_waitcnt lgkmcnt(0)
	v_mfma_f32_16x16x32_bf16 v[36:39], v[44:47], v[24:27], v[36:39]
	ds_read_b128 v[40:43], v213 offset:448
	ds_read_b128 v[44:47], v213 offset:35264
	s_waitcnt lgkmcnt(1)
	v_mfma_f32_16x16x32_bf16 v[32:35], v[40:43], v[28:31], v[32:35]
	s_waitcnt lgkmcnt(0)
	v_mfma_f32_16x16x32_bf16 v[36:39], v[44:47], v[28:31], v[36:39]
	ds_read_b128 v[40:43], v213 offset:8704
	ds_read_b128 v[44:47], v213 offset:43520
	ds_read_b128 v[48:51], v213 offset:8768
	ds_read_b128 v[52:55], v213 offset:43584
	s_waitcnt lgkmcnt(3)
	v_mfma_f32_16x16x32_bf16 v[40:43], v[40:43], v[0:3], 0
	s_waitcnt lgkmcnt(2)
	v_mfma_f32_16x16x32_bf16 v[44:47], v[44:47], v[0:3], 0
	s_waitcnt lgkmcnt(1)
	v_mfma_f32_16x16x32_bf16 v[40:43], v[48:51], v[4:7], v[40:43]
	s_waitcnt lgkmcnt(0)
	v_mfma_f32_16x16x32_bf16 v[44:47], v[52:55], v[4:7], v[44:47]
	ds_read_b128 v[48:51], v213 offset:8832
	ds_read_b128 v[52:55], v213 offset:43648
	s_waitcnt lgkmcnt(1)
	v_mfma_f32_16x16x32_bf16 v[40:43], v[48:51], v[8:11], v[40:43]
	s_waitcnt lgkmcnt(0)
	v_mfma_f32_16x16x32_bf16 v[44:47], v[52:55], v[8:11], v[44:47]
	ds_read_b128 v[48:51], v213 offset:8896
	ds_read_b128 v[52:55], v213 offset:43712
	s_waitcnt lgkmcnt(1)
	v_mfma_f32_16x16x32_bf16 v[40:43], v[48:51], v[12:15], v[40:43]
	s_waitcnt lgkmcnt(0)
	v_mfma_f32_16x16x32_bf16 v[44:47], v[52:55], v[12:15], v[44:47]
	ds_read_b128 v[48:51], v213 offset:8960
	ds_read_b128 v[52:55], v213 offset:43776
	s_waitcnt lgkmcnt(1)
	v_mfma_f32_16x16x32_bf16 v[40:43], v[48:51], v[16:19], v[40:43]
	s_waitcnt lgkmcnt(0)
	v_mfma_f32_16x16x32_bf16 v[44:47], v[52:55], v[16:19], v[44:47]
	ds_read_b128 v[48:51], v213 offset:9024
	ds_read_b128 v[52:55], v213 offset:43840
	s_waitcnt lgkmcnt(1)
	v_mfma_f32_16x16x32_bf16 v[40:43], v[48:51], v[20:23], v[40:43]
	s_waitcnt lgkmcnt(0)
	v_mfma_f32_16x16x32_bf16 v[44:47], v[52:55], v[20:23], v[44:47]
	ds_read_b128 v[48:51], v213 offset:9088
	ds_read_b128 v[52:55], v213 offset:43904
	s_waitcnt lgkmcnt(1)
	v_mfma_f32_16x16x32_bf16 v[40:43], v[48:51], v[24:27], v[40:43]
	s_waitcnt lgkmcnt(0)
	v_mfma_f32_16x16x32_bf16 v[44:47], v[52:55], v[24:27], v[44:47]
	ds_read_b128 v[48:51], v213 offset:9152
	ds_read_b128 v[52:55], v213 offset:43968
	s_waitcnt lgkmcnt(1)
	v_mfma_f32_16x16x32_bf16 v[40:43], v[48:51], v[28:31], v[40:43]
	s_waitcnt lgkmcnt(0)
	v_mfma_f32_16x16x32_bf16 v[44:47], v[52:55], v[28:31], v[44:47]
	ds_read_b128 v[48:51], v213 offset:17408
	ds_read_b128 v[52:55], v213 offset:52224
	ds_read_b128 v[56:59], v213 offset:17472
	ds_read_b128 v[60:63], v213 offset:52288
	s_waitcnt lgkmcnt(3)
	v_mfma_f32_16x16x32_bf16 v[48:51], v[48:51], v[0:3], 0
	s_waitcnt lgkmcnt(2)
	v_mfma_f32_16x16x32_bf16 v[52:55], v[52:55], v[0:3], 0
	s_waitcnt lgkmcnt(1)
	v_mfma_f32_16x16x32_bf16 v[48:51], v[56:59], v[4:7], v[48:51]
	s_waitcnt lgkmcnt(0)
	v_mfma_f32_16x16x32_bf16 v[52:55], v[60:63], v[4:7], v[52:55]
	ds_read_b128 v[56:59], v213 offset:17536
	ds_read_b128 v[60:63], v213 offset:52352
	s_waitcnt lgkmcnt(1)
	v_mfma_f32_16x16x32_bf16 v[48:51], v[56:59], v[8:11], v[48:51]
	s_waitcnt lgkmcnt(0)
	v_mfma_f32_16x16x32_bf16 v[52:55], v[60:63], v[8:11], v[52:55]
	ds_read_b128 v[56:59], v213 offset:17600
	ds_read_b128 v[60:63], v213 offset:52416
	s_waitcnt lgkmcnt(1)
	v_mfma_f32_16x16x32_bf16 v[48:51], v[56:59], v[12:15], v[48:51]
	s_waitcnt lgkmcnt(0)
	v_mfma_f32_16x16x32_bf16 v[52:55], v[60:63], v[12:15], v[52:55]
	ds_read_b128 v[56:59], v213 offset:17664
	ds_read_b128 v[60:63], v213 offset:52480
	s_waitcnt lgkmcnt(1)
	v_mfma_f32_16x16x32_bf16 v[48:51], v[56:59], v[16:19], v[48:51]
	s_waitcnt lgkmcnt(0)
	v_mfma_f32_16x16x32_bf16 v[52:55], v[60:63], v[16:19], v[52:55]
	ds_read_b128 v[56:59], v213 offset:17728
	ds_read_b128 v[60:63], v213 offset:52544
	s_waitcnt lgkmcnt(1)
	v_mfma_f32_16x16x32_bf16 v[48:51], v[56:59], v[20:23], v[48:51]
	s_waitcnt lgkmcnt(0)
	v_mfma_f32_16x16x32_bf16 v[52:55], v[60:63], v[20:23], v[52:55]
	ds_read_b128 v[56:59], v213 offset:17792
	ds_read_b128 v[60:63], v213 offset:52608
	s_waitcnt lgkmcnt(1)
	v_mfma_f32_16x16x32_bf16 v[48:51], v[56:59], v[24:27], v[48:51]
	s_waitcnt lgkmcnt(0)
	v_mfma_f32_16x16x32_bf16 v[52:55], v[60:63], v[24:27], v[52:55]
	ds_read_b128 v[56:59], v213 offset:17856
	ds_read_b128 v[60:63], v213 offset:52672
	s_waitcnt lgkmcnt(1)
	v_mfma_f32_16x16x32_bf16 v[48:51], v[56:59], v[28:31], v[48:51]
	s_waitcnt lgkmcnt(0)
	v_mfma_f32_16x16x32_bf16 v[52:55], v[60:63], v[28:31], v[52:55]
	ds_read_b128 v[56:59], v213 offset:26112
	ds_read_b128 v[60:63], v213 offset:60928
	ds_read_b128 v[64:67], v213 offset:26176
	ds_read_b128 v[68:71], v213 offset:60992
	s_waitcnt lgkmcnt(3)
	v_mfma_f32_16x16x32_bf16 v[56:59], v[56:59], v[0:3], 0
	s_waitcnt lgkmcnt(2)
	v_mfma_f32_16x16x32_bf16 v[60:63], v[60:63], v[0:3], 0
	s_waitcnt lgkmcnt(1)
	v_mfma_f32_16x16x32_bf16 v[56:59], v[64:67], v[4:7], v[56:59]
	s_waitcnt lgkmcnt(0)
	v_mfma_f32_16x16x32_bf16 v[60:63], v[68:71], v[4:7], v[60:63]
	ds_read_b128 v[64:67], v213 offset:26240
	ds_read_b128 v[68:71], v213 offset:61056
	s_waitcnt lgkmcnt(1)
	v_mfma_f32_16x16x32_bf16 v[56:59], v[64:67], v[8:11], v[56:59]
	s_waitcnt lgkmcnt(0)
	v_mfma_f32_16x16x32_bf16 v[60:63], v[68:71], v[8:11], v[60:63]
	ds_read_b128 v[64:67], v213 offset:26304
	ds_read_b128 v[68:71], v213 offset:61120
	s_waitcnt lgkmcnt(1)
	v_mfma_f32_16x16x32_bf16 v[56:59], v[64:67], v[12:15], v[56:59]
	s_waitcnt lgkmcnt(0)
	v_mfma_f32_16x16x32_bf16 v[60:63], v[68:71], v[12:15], v[60:63]
	ds_read_b128 v[64:67], v213 offset:26368
	ds_read_b128 v[68:71], v213 offset:61184
	s_waitcnt lgkmcnt(1)
	v_mfma_f32_16x16x32_bf16 v[56:59], v[64:67], v[16:19], v[56:59]
	s_waitcnt lgkmcnt(0)
	v_mfma_f32_16x16x32_bf16 v[60:63], v[68:71], v[16:19], v[60:63]
	ds_read_b128 v[64:67], v213 offset:26432
	ds_read_b128 v[68:71], v213 offset:61248
	s_waitcnt lgkmcnt(1)
	v_mfma_f32_16x16x32_bf16 v[56:59], v[64:67], v[20:23], v[56:59]
	s_waitcnt lgkmcnt(0)
	v_mfma_f32_16x16x32_bf16 v[60:63], v[68:71], v[20:23], v[60:63]
	ds_read_b128 v[64:67], v213 offset:26496
	ds_read_b128 v[68:71], v213 offset:61312
	s_waitcnt lgkmcnt(1)
	v_mfma_f32_16x16x32_bf16 v[56:59], v[64:67], v[24:27], v[56:59]
	s_waitcnt lgkmcnt(0)
	v_mfma_f32_16x16x32_bf16 v[60:63], v[68:71], v[24:27], v[60:63]
	ds_read_b128 v[64:67], v213 offset:26560
	ds_read_b128 v[68:71], v213 offset:61376
	s_waitcnt vmcnt(0)
	s_waitcnt lgkmcnt(1)
	v_mfma_f32_16x16x32_bf16 v[56:59], v[64:67], v[28:31], v[56:59]
	v_lshl_add_u64 v[64:65], s[58:59], 0, v[132:133]
	s_waitcnt lgkmcnt(0)
	s_barrier
	global_load_lds_dwordx4 v[64:65], off
	v_lshl_add_u64 v[64:65], s[60:61], 0, v[132:133]
	s_mov_b32 m0, s48
	v_mfma_f32_16x16x32_bf16 v[60:63], v[68:71], v[28:31], v[60:63]
	global_load_lds_dwordx4 v[64:65], off
	v_lshl_add_u64 v[64:65], s[58:59], 0, v[134:135]
	s_mov_b32 m0, s49
	s_nop 0
	global_load_lds_dwordx4 v[64:65], off
	v_lshl_add_u64 v[64:65], s[60:61], 0, v[134:135]
	s_mov_b32 m0, s62
	s_nop 0
	global_load_lds_dwordx4 v[64:65], off
	v_lshl_add_u64 v[64:65], s[58:59], 0, v[136:137]
	s_mov_b32 m0, s63
	s_nop 0
	global_load_lds_dwordx4 v[64:65], off
	v_lshl_add_u64 v[64:65], s[60:61], 0, v[136:137]
	s_mov_b32 m0, s64
	s_nop 0
	global_load_lds_dwordx4 v[64:65], off
	v_lshl_add_u64 v[64:65], s[58:59], 0, v[138:139]
	s_mov_b32 m0, s65
	s_nop 0
	global_load_lds_dwordx4 v[64:65], off
	v_lshl_add_u64 v[64:65], s[60:61], 0, v[138:139]
	s_mov_b32 m0, s66
	s_nop 0
	global_load_lds_dwordx4 v[64:65], off
	s_cbranch_vccnz .LBB0_1088
	s_mov_b32 m0, s82
	v_lshl_add_u64 v[66:67], s[58:59], 0, v[140:141]
	v_lshl_add_u64 v[64:65], s[60:61], 0, v[140:141]
	global_load_lds_dwordx4 v[66:67], off
	s_add_i32 m0, s82, 0x8800
	s_nop 0
	global_load_lds_dwordx4 v[64:65], off
.LBB0_1088:
	ds_read_b128 v[64:67], v225
	ds_read_b128 v[68:71], v225 offset:64
	ds_read_b128 v[72:75], v226
	ds_read_b128 v[80:83], v226 offset:64
	v_add_u32_e32 v168, v217, v214
	v_add_u32_e32 v167, v218, v214
	s_waitcnt lgkmcnt(0)
	v_mfma_f32_16x16x32_bf16 v[64:67], v[64:67], v[0:3], 0
	v_add_u32_e32 v166, v217, v215
	v_add_u32_e32 v164, v218, v215
	v_add_u32_e32 v163, v217, v216
	v_mfma_f32_16x16x32_bf16 v[72:75], v[72:75], v[0:3], 0
	v_add_u32_e32 v165, v218, v216
	s_add_u32 s58, s42, 0x18000
	s_addc_u32 s59, s96, 0
	v_mfma_f32_16x16x32_bf16 v[64:67], v[68:71], v[4:7], v[64:67]
	s_add_u32 s60, s97, 0x18000
	s_mov_b32 m0, s74
	s_addc_u32 s61, s18, 0
	v_mfma_f32_16x16x32_bf16 v[68:71], v[80:83], v[4:7], v[72:75]
	s_nop 2
	ds_read_b128 v[72:75], v225 offset:128
	ds_read_b128 v[80:83], v225 offset:192
	v_lshl_add_u64 v[76:77], s[58:59], 0, v[132:133]
	s_and_b64 vcc, exec, s[4:5]
	s_waitcnt lgkmcnt(1)
	v_mfma_f32_16x16x32_bf16 v[64:67], v[72:75], v[8:11], v[64:67]
	ds_read_b128 v[72:75], v226 offset:128
	ds_read_b128 v[84:87], v226 offset:192
	s_waitcnt lgkmcnt(1)
	v_mfma_f32_16x16x32_bf16 v[68:71], v[72:75], v[8:11], v[68:71]
	v_mfma_f32_16x16x32_bf16 v[64:67], v[80:83], v[12:15], v[64:67]
	ds_read_b128 v[72:75], v225 offset:256
	ds_read_b128 v[80:83], v225 offset:320
	s_waitcnt lgkmcnt(2)
	v_mfma_f32_16x16x32_bf16 v[68:71], v[84:87], v[12:15], v[68:71]
	s_waitcnt lgkmcnt(1)
	v_mfma_f32_16x16x32_bf16 v[64:67], v[72:75], v[16:19], v[64:67]
	ds_read_b128 v[72:75], v226 offset:256
	ds_read_b128 v[84:87], v226 offset:320
	s_waitcnt lgkmcnt(1)
	v_mfma_f32_16x16x32_bf16 v[68:71], v[72:75], v[16:19], v[68:71]
	v_mfma_f32_16x16x32_bf16 v[64:67], v[80:83], v[20:23], v[64:67]
	ds_read_b128 v[72:75], v225 offset:384
	ds_read_b128 v[80:83], v225 offset:448
	s_waitcnt lgkmcnt(2)
	v_mfma_f32_16x16x32_bf16 v[68:71], v[84:87], v[20:23], v[68:71]
	s_waitcnt lgkmcnt(1)
	v_mfma_f32_16x16x32_bf16 v[64:67], v[72:75], v[24:27], v[64:67]
	ds_read_b128 v[72:75], v226 offset:384
	ds_read_b128 v[84:87], v226 offset:448
	s_waitcnt lgkmcnt(1)
	v_mfma_f32_16x16x32_bf16 v[68:71], v[72:75], v[24:27], v[68:71]
	v_mfma_f32_16x16x32_bf16 v[80:83], v[80:83], v[28:31], v[64:67]
	s_nop 2
	ds_read_b128 v[64:67], v168
	s_waitcnt lgkmcnt(1)
	v_mfma_f32_16x16x32_bf16 v[84:87], v[84:87], v[28:31], v[68:71]
	s_nop 2
	ds_read_b128 v[68:71], v167
	s_waitcnt lgkmcnt(1)
	v_mfma_f32_16x16x32_bf16 v[64:67], v[64:67], v[0:3], 0
	ds_read_b128 v[72:75], v227 offset:64
	ds_read_b128 v[88:91], v227 offset:128
	s_waitcnt lgkmcnt(2)
	v_mfma_f32_16x16x32_bf16 v[68:71], v[68:71], v[0:3], 0
	s_waitcnt lgkmcnt(1)
	v_mfma_f32_16x16x32_bf16 v[64:67], v[72:75], v[4:7], v[64:67]
	ds_read_b128 v[72:75], v228 offset:64
	ds_read_b128 v[92:95], v227 offset:448
	s_waitcnt lgkmcnt(1)
	v_mfma_f32_16x16x32_bf16 v[68:71], v[72:75], v[4:7], v[68:71]
	v_mfma_f32_16x16x32_bf16 v[64:67], v[88:91], v[8:11], v[64:67]
	ds_read_b128 v[72:75], v228 offset:128
	ds_read_b128 v[88:91], v228 offset:192
	s_waitcnt lgkmcnt(1)
	v_mfma_f32_16x16x32_bf16 v[68:71], v[72:75], v[8:11], v[68:71]
	ds_read_b128 v[72:75], v227 offset:192
	ds_read_b128 v[96:99], v227 offset:256
	s_waitcnt lgkmcnt(1)
	v_mfma_f32_16x16x32_bf16 v[64:67], v[72:75], v[12:15], v[64:67]
	v_mfma_f32_16x16x32_bf16 v[68:71], v[88:91], v[12:15], v[68:71]
	ds_read_b128 v[72:75], v228 offset:256
	ds_read_b128 v[88:91], v228 offset:320
	s_waitcnt lgkmcnt(2)
	v_mfma_f32_16x16x32_bf16 v[64:67], v[96:99], v[16:19], v[64:67]
	s_waitcnt lgkmcnt(1)
	v_mfma_f32_16x16x32_bf16 v[68:71], v[72:75], v[16:19], v[68:71]
	ds_read_b128 v[72:75], v227 offset:320
	ds_read_b128 v[96:99], v227 offset:384
	s_waitcnt lgkmcnt(1)
	v_mfma_f32_16x16x32_bf16 v[64:67], v[72:75], v[20:23], v[64:67]
	v_mfma_f32_16x16x32_bf16 v[68:71], v[88:91], v[20:23], v[68:71]
	s_waitcnt lgkmcnt(0)
	v_mfma_f32_16x16x32_bf16 v[64:67], v[96:99], v[24:27], v[64:67]
	ds_read_b128 v[72:75], v228 offset:384
	ds_read_b128 v[96:99], v228 offset:448
	s_waitcnt lgkmcnt(1)
	v_mfma_f32_16x16x32_bf16 v[68:71], v[72:75], v[24:27], v[68:71]
	v_mfma_f32_16x16x32_bf16 v[88:91], v[92:95], v[28:31], v[64:67]
	s_nop 2
	ds_read_b128 v[64:67], v166
	s_waitcnt lgkmcnt(1)
	v_mfma_f32_16x16x32_bf16 v[96:99], v[96:99], v[28:31], v[68:71]
	s_nop 2
	ds_read_b128 v[68:71], v164
	s_waitcnt lgkmcnt(1)
	v_mfma_f32_16x16x32_bf16 v[64:67], v[64:67], v[0:3], 0
	ds_read_b128 v[72:75], v229 offset:64
	ds_read_b128 v[92:95], v229 offset:128
	s_waitcnt lgkmcnt(2)
	v_mfma_f32_16x16x32_bf16 v[68:71], v[68:71], v[0:3], 0
	s_waitcnt lgkmcnt(1)
	v_mfma_f32_16x16x32_bf16 v[64:67], v[72:75], v[4:7], v[64:67]
	ds_read_b128 v[72:75], v232 offset:64
	ds_read_b128 v[100:103], v229 offset:448
	s_waitcnt lgkmcnt(1)
	v_mfma_f32_16x16x32_bf16 v[68:71], v[72:75], v[4:7], v[68:71]
	v_mfma_f32_16x16x32_bf16 v[64:67], v[92:95], v[8:11], v[64:67]
	ds_read_b128 v[72:75], v232 offset:128
	ds_read_b128 v[92:95], v232 offset:192
	s_waitcnt lgkmcnt(1)
	v_mfma_f32_16x16x32_bf16 v[68:71], v[72:75], v[8:11], v[68:71]
	ds_read_b128 v[72:75], v229 offset:192
	ds_read_b128 v[104:107], v229 offset:256
	s_waitcnt lgkmcnt(1)
	v_mfma_f32_16x16x32_bf16 v[64:67], v[72:75], v[12:15], v[64:67]
	v_mfma_f32_16x16x32_bf16 v[68:71], v[92:95], v[12:15], v[68:71]
	ds_read_b128 v[72:75], v232 offset:256
	ds_read_b128 v[92:95], v232 offset:320
	s_waitcnt lgkmcnt(2)
	v_mfma_f32_16x16x32_bf16 v[64:67], v[104:107], v[16:19], v[64:67]
	s_waitcnt lgkmcnt(1)
	v_mfma_f32_16x16x32_bf16 v[68:71], v[72:75], v[16:19], v[68:71]
	ds_read_b128 v[72:75], v229 offset:320
	ds_read_b128 v[104:107], v229 offset:384
	s_waitcnt lgkmcnt(1)
	v_mfma_f32_16x16x32_bf16 v[64:67], v[72:75], v[20:23], v[64:67]
	v_mfma_f32_16x16x32_bf16 v[68:71], v[92:95], v[20:23], v[68:71]
	ds_read_b128 v[72:75], v232 offset:384
	ds_read_b128 v[92:95], v232 offset:448
	s_waitcnt lgkmcnt(2)
	v_mfma_f32_16x16x32_bf16 v[64:67], v[104:107], v[24:27], v[64:67]
	s_waitcnt lgkmcnt(1)
	v_mfma_f32_16x16x32_bf16 v[68:71], v[72:75], v[24:27], v[68:71]
	v_mfma_f32_16x16x32_bf16 v[100:103], v[100:103], v[28:31], v[64:67]
	s_nop 4
	ds_read_b128 v[64:67], v163
	s_waitcnt lgkmcnt(1)
	v_mfma_f32_16x16x32_bf16 v[104:107], v[92:95], v[28:31], v[68:71]
	s_nop 2
	ds_read_b128 v[68:71], v165
	ds_read_b128 v[72:75], v233 offset:64
	ds_read_b128 v[92:95], v234 offset:64
	ds_read_b128 v[108:111], v233 offset:128
	s_waitcnt lgkmcnt(3)
	v_mfma_f32_16x16x32_bf16 v[68:71], v[68:71], v[0:3], 0
	ds_read_b128 v[112:115], v234 offset:128
	ds_read_b128 v[116:119], v234 offset:192
	ds_read_b128 v[120:123], v233 offset:192
	ds_read_b128 v[124:127], v233 offset:256
	s_waitcnt lgkmcnt(5)
	v_mfma_f32_16x16x32_bf16 v[68:71], v[92:95], v[4:7], v[68:71]
	s_waitcnt lgkmcnt(3)
	v_mfma_f32_16x16x32_bf16 v[68:71], v[112:115], v[8:11], v[68:71]
	v_mfma_f32_16x16x32_bf16 v[64:67], v[64:67], v[0:3], 0
	s_waitcnt lgkmcnt(2)
	v_mfma_f32_16x16x32_bf16 v[68:71], v[116:119], v[12:15], v[68:71]
	v_mfma_f32_16x16x32_bf16 v[64:67], v[72:75], v[4:7], v[64:67]
	ds_read_b128 v[72:75], v234 offset:256
	ds_read_b128 v[128:131], v234 offset:320
	ds_read_b128 v[170:173], v233 offset:448
	ds_read_b128 v[92:95], v233 offset:320
	ds_read_b128 v[174:177], v233 offset:384
	ds_read_b128 v[178:181], v234 offset:384
	ds_read_b128 v[236:239], v234 offset:448
	s_waitcnt vmcnt(0)
	s_waitcnt vmcnt(0)
	s_waitcnt lgkmcnt(0)
	s_barrier
	global_load_lds_dwordx4 v[76:77], off
	v_lshl_add_u64 v[76:77], s[60:61], 0, v[132:133]
	s_mov_b32 m0, s75
	v_mfma_f32_16x16x32_bf16 v[68:71], v[72:75], v[16:19], v[68:71]
	global_load_lds_dwordx4 v[76:77], off
	v_lshl_add_u64 v[76:77], s[58:59], 0, v[134:135]
	s_mov_b32 m0, s76
	v_lshl_add_u64 v[72:73], s[60:61], 0, v[134:135]
	global_load_lds_dwordx4 v[76:77], off
	s_mov_b32 m0, s77
	v_mfma_f32_16x16x32_bf16 v[64:67], v[108:111], v[8:11], v[64:67]
	global_load_lds_dwordx4 v[72:73], off
	v_lshl_add_u64 v[72:73], s[58:59], 0, v[136:137]
	s_mov_b32 m0, s78
	v_mfma_f32_16x16x32_bf16 v[64:67], v[120:123], v[12:15], v[64:67]
	global_load_lds_dwordx4 v[72:73], off
	v_lshl_add_u64 v[72:73], s[60:61], 0, v[136:137]
	s_mov_b32 m0, s79
	v_mfma_f32_16x16x32_bf16 v[64:67], v[124:127], v[16:19], v[64:67]
	global_load_lds_dwordx4 v[72:73], off
	v_lshl_add_u64 v[72:73], s[58:59], 0, v[138:139]
	s_mov_b32 m0, s80
	v_mfma_f32_16x16x32_bf16 v[64:67], v[92:95], v[20:23], v[64:67]
	global_load_lds_dwordx4 v[72:73], off
	v_lshl_add_u64 v[72:73], s[60:61], 0, v[138:139]
	s_mov_b32 m0, s81
	v_mfma_f32_16x16x32_bf16 v[68:71], v[128:131], v[20:23], v[68:71]
	global_load_lds_dwordx4 v[72:73], off
	v_mfma_f32_16x16x32_bf16 v[64:67], v[174:177], v[24:27], v[64:67]
	v_mfma_f32_16x16x32_bf16 v[68:71], v[178:181], v[24:27], v[68:71]
	v_mfma_f32_16x16x32_bf16 v[108:111], v[170:173], v[28:31], v[64:67]
	v_mfma_f32_16x16x32_bf16 v[112:115], v[236:239], v[28:31], v[68:71]
	s_cbranch_vccnz .LBB0_1090
	s_mov_b32 m0, s83
	s_nop 2
	v_lshl_add_u64 v[66:67], s[58:59], 0, v[140:141]
	v_lshl_add_u64 v[64:65], s[60:61], 0, v[140:141]
	global_load_lds_dwordx4 v[66:67], off
	s_mov_b32 m0, s84
	s_nop 0
	global_load_lds_dwordx4 v[64:65], off
.LBB0_1090:
	s_nop 3
	ds_read_b128 v[64:67], v213
	ds_read_b128 v[68:71], v213 offset:34816
	ds_read_b128 v[72:75], v213 offset:64
	ds_read_b128 v[92:95], v213 offset:34880
	s_lshl_b32 s18, s95, 9
	s_or_b32 s54, s54, s18
	s_waitcnt lgkmcnt(0)
	v_mfma_f32_16x16x32_bf16 v[64:67], v[64:67], v[0:3], 0
	s_lshl_b32 s42, s93, 8
	s_lshl_b64 s[18:19], s[54:55], 11
	s_add_u32 s34, s38, s18
	v_mfma_f32_16x16x32_bf16 v[68:71], v[68:71], v[0:3], 0
	s_addc_u32 s35, s39, s19
	s_lshl_b32 s54, s94, 9
	s_and_b32 s58, s54, 0x600
	v_mfma_f32_16x16x32_bf16 v[64:67], v[72:75], v[4:7], v[64:67]
	s_add_u32 s54, s34, s58
	s_addc_u32 s55, s35, 0
	s_add_u32 s18, s56, s18
	v_mfma_f32_16x16x32_bf16 v[68:71], v[92:95], v[4:7], v[68:71]
	ds_read_b128 v[72:75], v213 offset:128
	ds_read_b128 v[92:95], v213 offset:34944
	s_addc_u32 s19, s57, s19
	s_add_u32 s58, s18, s58
	s_waitcnt lgkmcnt(1)
	v_mfma_f32_16x16x32_bf16 v[64:67], v[72:75], v[8:11], v[64:67]
	s_addc_u32 s59, s19, 0
	v_lshl_add_u64 v[76:77], s[54:55], 0, v[148:149]
	s_mov_b32 m0, s21
	s_waitcnt lgkmcnt(0)
	v_mfma_f32_16x16x32_bf16 v[68:71], v[92:95], v[8:11], v[68:71]
	ds_read_b128 v[72:75], v213 offset:192
	ds_read_b128 v[92:95], v213 offset:35008
	s_and_b64 vcc, exec, s[4:5]
	s_waitcnt lgkmcnt(1)
	v_mfma_f32_16x16x32_bf16 v[64:67], v[72:75], v[12:15], v[64:67]
	s_waitcnt lgkmcnt(0)
	v_mfma_f32_16x16x32_bf16 v[68:71], v[92:95], v[12:15], v[68:71]
	ds_read_b128 v[72:75], v213 offset:256
	ds_read_b128 v[92:95], v213 offset:35072
	s_waitcnt lgkmcnt(1)
	v_mfma_f32_16x16x32_bf16 v[64:67], v[72:75], v[16:19], v[64:67]
	s_waitcnt lgkmcnt(0)
	v_mfma_f32_16x16x32_bf16 v[68:71], v[92:95], v[16:19], v[68:71]
	ds_read_b128 v[72:75], v213 offset:320
	ds_read_b128 v[92:95], v213 offset:35136
	s_waitcnt lgkmcnt(1)
	v_mfma_f32_16x16x32_bf16 v[64:67], v[72:75], v[20:23], v[64:67]
	s_waitcnt lgkmcnt(0)
	v_mfma_f32_16x16x32_bf16 v[68:71], v[92:95], v[20:23], v[68:71]
	ds_read_b128 v[72:75], v213 offset:384
	ds_read_b128 v[92:95], v213 offset:35200
	s_waitcnt lgkmcnt(1)
	v_mfma_f32_16x16x32_bf16 v[64:67], v[72:75], v[24:27], v[64:67]
	s_waitcnt lgkmcnt(0)
	v_mfma_f32_16x16x32_bf16 v[68:71], v[92:95], v[24:27], v[68:71]
	ds_read_b128 v[72:75], v213 offset:448
	ds_read_b128 v[92:95], v213 offset:35264
	s_waitcnt lgkmcnt(1)
	v_mfma_f32_16x16x32_bf16 v[64:67], v[72:75], v[28:31], v[64:67]
	s_waitcnt lgkmcnt(0)
	v_mfma_f32_16x16x32_bf16 v[68:71], v[92:95], v[28:31], v[68:71]
	ds_read_b128 v[72:75], v213 offset:8704
	ds_read_b128 v[92:95], v213 offset:43520
	ds_read_b128 v[116:119], v213 offset:8768
	ds_read_b128 v[120:123], v213 offset:43584
	s_waitcnt lgkmcnt(3)
	v_mfma_f32_16x16x32_bf16 v[72:75], v[72:75], v[0:3], 0
	s_waitcnt lgkmcnt(2)
	v_mfma_f32_16x16x32_bf16 v[92:95], v[92:95], v[0:3], 0
	s_waitcnt lgkmcnt(1)
	v_mfma_f32_16x16x32_bf16 v[72:75], v[116:119], v[4:7], v[72:75]
	s_waitcnt lgkmcnt(0)
	v_mfma_f32_16x16x32_bf16 v[92:95], v[120:123], v[4:7], v[92:95]
	ds_read_b128 v[116:119], v213 offset:8832
	ds_read_b128 v[120:123], v213 offset:43648
	s_waitcnt lgkmcnt(1)
	v_mfma_f32_16x16x32_bf16 v[72:75], v[116:119], v[8:11], v[72:75]
	s_waitcnt lgkmcnt(0)
	v_mfma_f32_16x16x32_bf16 v[92:95], v[120:123], v[8:11], v[92:95]
	ds_read_b128 v[116:119], v213 offset:8896
	ds_read_b128 v[120:123], v213 offset:43712
	s_waitcnt lgkmcnt(1)
	v_mfma_f32_16x16x32_bf16 v[72:75], v[116:119], v[12:15], v[72:75]
	s_waitcnt lgkmcnt(0)
	v_mfma_f32_16x16x32_bf16 v[92:95], v[120:123], v[12:15], v[92:95]
	ds_read_b128 v[116:119], v213 offset:8960
	ds_read_b128 v[120:123], v213 offset:43776
	s_waitcnt lgkmcnt(1)
	v_mfma_f32_16x16x32_bf16 v[72:75], v[116:119], v[16:19], v[72:75]
	s_waitcnt lgkmcnt(0)
	v_mfma_f32_16x16x32_bf16 v[92:95], v[120:123], v[16:19], v[92:95]
	ds_read_b128 v[116:119], v213 offset:9024
	ds_read_b128 v[120:123], v213 offset:43840
	s_waitcnt lgkmcnt(1)
	v_mfma_f32_16x16x32_bf16 v[72:75], v[116:119], v[20:23], v[72:75]
	s_waitcnt lgkmcnt(0)
	v_mfma_f32_16x16x32_bf16 v[92:95], v[120:123], v[20:23], v[92:95]
	ds_read_b128 v[116:119], v213 offset:9088
	ds_read_b128 v[120:123], v213 offset:43904
	s_waitcnt lgkmcnt(1)
	v_mfma_f32_16x16x32_bf16 v[72:75], v[116:119], v[24:27], v[72:75]
	s_waitcnt lgkmcnt(0)
	v_mfma_f32_16x16x32_bf16 v[92:95], v[120:123], v[24:27], v[92:95]
	ds_read_b128 v[116:119], v213 offset:9152
	ds_read_b128 v[120:123], v213 offset:43968
	s_waitcnt lgkmcnt(1)
	v_mfma_f32_16x16x32_bf16 v[72:75], v[116:119], v[28:31], v[72:75]
	s_waitcnt lgkmcnt(0)
	v_mfma_f32_16x16x32_bf16 v[92:95], v[120:123], v[28:31], v[92:95]
	ds_read_b128 v[116:119], v213 offset:17408
	ds_read_b128 v[120:123], v213 offset:52224
	ds_read_b128 v[124:127], v213 offset:17472
	ds_read_b128 v[128:131], v213 offset:52288
	s_waitcnt lgkmcnt(3)
	v_mfma_f32_16x16x32_bf16 v[116:119], v[116:119], v[0:3], 0
	s_waitcnt lgkmcnt(2)
	v_mfma_f32_16x16x32_bf16 v[120:123], v[120:123], v[0:3], 0
	s_waitcnt lgkmcnt(1)
	v_mfma_f32_16x16x32_bf16 v[116:119], v[124:127], v[4:7], v[116:119]
	s_waitcnt lgkmcnt(0)
	v_mfma_f32_16x16x32_bf16 v[120:123], v[128:131], v[4:7], v[120:123]
	ds_read_b128 v[124:127], v213 offset:17536
	ds_read_b128 v[128:131], v213 offset:52352
	s_waitcnt lgkmcnt(1)
	v_mfma_f32_16x16x32_bf16 v[116:119], v[124:127], v[8:11], v[116:119]
	s_waitcnt lgkmcnt(0)
	v_mfma_f32_16x16x32_bf16 v[120:123], v[128:131], v[8:11], v[120:123]
	ds_read_b128 v[124:127], v213 offset:17600
	ds_read_b128 v[128:131], v213 offset:52416
	s_waitcnt lgkmcnt(1)
	v_mfma_f32_16x16x32_bf16 v[116:119], v[124:127], v[12:15], v[116:119]
	s_waitcnt lgkmcnt(0)
	v_mfma_f32_16x16x32_bf16 v[120:123], v[128:131], v[12:15], v[120:123]
	ds_read_b128 v[124:127], v213 offset:17664
	ds_read_b128 v[128:131], v213 offset:52480
	s_waitcnt lgkmcnt(1)
	v_mfma_f32_16x16x32_bf16 v[116:119], v[124:127], v[16:19], v[116:119]
	s_waitcnt lgkmcnt(0)
	v_mfma_f32_16x16x32_bf16 v[120:123], v[128:131], v[16:19], v[120:123]
	ds_read_b128 v[124:127], v213 offset:17728
	ds_read_b128 v[128:131], v213 offset:52544
	s_waitcnt lgkmcnt(1)
	v_mfma_f32_16x16x32_bf16 v[116:119], v[124:127], v[20:23], v[116:119]
	s_waitcnt lgkmcnt(0)
	v_mfma_f32_16x16x32_bf16 v[120:123], v[128:131], v[20:23], v[120:123]
	ds_read_b128 v[124:127], v213 offset:17792
	ds_read_b128 v[128:131], v213 offset:52608
	s_waitcnt lgkmcnt(1)
	v_mfma_f32_16x16x32_bf16 v[116:119], v[124:127], v[24:27], v[116:119]
	s_waitcnt lgkmcnt(0)
	v_mfma_f32_16x16x32_bf16 v[120:123], v[128:131], v[24:27], v[120:123]
	ds_read_b128 v[124:127], v213 offset:17856
	ds_read_b128 v[128:131], v213 offset:52672
	s_waitcnt lgkmcnt(1)
	v_mfma_f32_16x16x32_bf16 v[116:119], v[124:127], v[28:31], v[116:119]
	s_waitcnt lgkmcnt(0)
	v_mfma_f32_16x16x32_bf16 v[120:123], v[128:131], v[28:31], v[120:123]
	ds_read_b128 v[124:127], v213 offset:26112
	ds_read_b128 v[128:131], v213 offset:60928
	ds_read_b128 v[170:173], v213 offset:26176
	ds_read_b128 v[174:177], v213 offset:60992
	s_waitcnt lgkmcnt(3)
	v_mfma_f32_16x16x32_bf16 v[124:127], v[124:127], v[0:3], 0
	s_waitcnt lgkmcnt(2)
	v_mfma_f32_16x16x32_bf16 v[128:131], v[128:131], v[0:3], 0
	s_waitcnt lgkmcnt(1)
	v_mfma_f32_16x16x32_bf16 v[124:127], v[170:173], v[4:7], v[124:127]
	s_waitcnt lgkmcnt(0)
	v_mfma_f32_16x16x32_bf16 v[128:131], v[174:177], v[4:7], v[128:131]
	ds_read_b128 v[170:173], v213 offset:26240
	ds_read_b128 v[174:177], v213 offset:61056
	s_waitcnt lgkmcnt(1)
	v_mfma_f32_16x16x32_bf16 v[124:127], v[170:173], v[8:11], v[124:127]
	s_waitcnt lgkmcnt(0)
	v_mfma_f32_16x16x32_bf16 v[128:131], v[174:177], v[8:11], v[128:131]
	ds_read_b128 v[170:173], v213 offset:26304
	ds_read_b128 v[174:177], v213 offset:61120
	s_waitcnt lgkmcnt(1)
	v_mfma_f32_16x16x32_bf16 v[124:127], v[170:173], v[12:15], v[124:127]
	s_waitcnt lgkmcnt(0)
	v_mfma_f32_16x16x32_bf16 v[128:131], v[174:177], v[12:15], v[128:131]
	ds_read_b128 v[170:173], v213 offset:26368
	ds_read_b128 v[174:177], v213 offset:61184
	s_waitcnt lgkmcnt(1)
	v_mfma_f32_16x16x32_bf16 v[124:127], v[170:173], v[16:19], v[124:127]
	s_waitcnt lgkmcnt(0)
	v_mfma_f32_16x16x32_bf16 v[128:131], v[174:177], v[16:19], v[128:131]
	ds_read_b128 v[170:173], v213 offset:26432
	ds_read_b128 v[174:177], v213 offset:61248
	s_waitcnt lgkmcnt(1)
	v_mfma_f32_16x16x32_bf16 v[124:127], v[170:173], v[20:23], v[124:127]
	s_waitcnt lgkmcnt(0)
	v_mfma_f32_16x16x32_bf16 v[128:131], v[174:177], v[20:23], v[128:131]
	ds_read_b128 v[170:173], v213 offset:26496
	ds_read_b128 v[174:177], v213 offset:61312
	s_waitcnt lgkmcnt(1)
	v_mfma_f32_16x16x32_bf16 v[124:127], v[170:173], v[24:27], v[124:127]
	s_waitcnt lgkmcnt(0)
	v_mfma_f32_16x16x32_bf16 v[128:131], v[174:177], v[24:27], v[128:131]
	ds_read_b128 v[170:173], v213 offset:26560
	ds_read_b128 v[174:177], v213 offset:61376
	s_waitcnt vmcnt(0)
	s_waitcnt vmcnt(0)
	s_waitcnt lgkmcnt(0)
	s_barrier
	global_load_lds_dwordx4 v[76:77], off
	v_lshl_add_u64 v[76:77], s[58:59], 0, v[148:149]
	s_mov_b32 m0, s48
	v_mfma_f32_16x16x32_bf16 v[124:127], v[170:173], v[28:31], v[124:127]
	global_load_lds_dwordx4 v[76:77], off
	v_lshl_add_u64 v[76:77], s[54:55], 0, v[150:151]
	s_mov_b32 m0, s49
	v_mfma_f32_16x16x32_bf16 v[128:131], v[174:177], v[28:31], v[128:131]
	global_load_lds_dwordx4 v[76:77], off
	v_lshl_add_u64 v[76:77], s[58:59], 0, v[150:151]
	s_mov_b32 m0, s62
	s_nop 0
	global_load_lds_dwordx4 v[76:77], off
	v_lshl_add_u64 v[76:77], s[54:55], 0, v[152:153]
	s_mov_b32 m0, s63
	s_nop 0
	global_load_lds_dwordx4 v[76:77], off
	v_lshl_add_u64 v[76:77], s[58:59], 0, v[152:153]
	s_mov_b32 m0, s64
	s_nop 0
	global_load_lds_dwordx4 v[76:77], off
	v_lshl_add_u64 v[76:77], s[54:55], 0, v[154:155]
	s_mov_b32 m0, s65
	s_nop 0
	global_load_lds_dwordx4 v[76:77], off
	v_lshl_add_u64 v[76:77], s[58:59], 0, v[154:155]
	s_mov_b32 m0, s66
	s_nop 0
	global_load_lds_dwordx4 v[76:77], off
	s_cbranch_vccnz .LBB0_1092
	s_mov_b32 m0, s82
	v_lshl_add_u64 v[170:171], s[54:55], 0, v[156:157]
	v_lshl_add_u64 v[76:77], s[58:59], 0, v[156:157]
	global_load_lds_dwordx4 v[170:171], off
	s_add_i32 m0, s82, 0x8800
	s_nop 0
	global_load_lds_dwordx4 v[76:77], off
.LBB0_1092:
	v_add_f32_e32 v76, -1.0, v159
	v_sub_f32_e32 v77, v76, v159
	v_add_f32_e32 v77, 1.0, v77
	v_sub_f32_e32 v76, v79, v76
	v_add_f32_e32 v169, v76, v77
	v_cvt_f64_f32_e32 v[76:77], v159
	v_frexp_exp_i32_f64_e32 v76, v[76:77]
	v_subbrev_co_u32_e64 v176, vcc, 0, v76, s[16:17]
	v_sub_u32_e32 v76, 0, v176
	v_ldexp_f32 v77, v159, v76
	v_add_f32_e32 v159, -1.0, v77
	v_add_f32_e32 v170, 1.0, v77
	v_ldexp_f32 v76, v169, v76
	v_add_f32_e32 v169, 1.0, v159
	v_add_f32_e32 v171, -1.0, v170
	v_sub_f32_e32 v169, v77, v169
	v_sub_f32_e32 v77, v77, v171
	v_add_f32_e32 v169, v76, v169
	v_add_f32_e32 v76, v76, v77
	v_add_f32_e32 v177, v170, v76
	v_rcp_f32_e32 v179, v177
	v_sub_f32_e32 v77, v170, v177
	v_add_f32_e32 v178, v76, v77
	v_add_f32_e32 v77, v159, v169
	v_sub_f32_e32 v76, v159, v77
	v_add_f32_e32 v159, v169, v76
	v_mul_f32_e32 v169, v77, v179
	v_mul_f32_e32 v170, v177, v169
	v_fma_f32 v172, v169, v177, -v170
	v_fmac_f32_e32 v172, v169, v178
	v_add_f32_e32 v76, v170, v172
	v_sub_f32_e32 v171, v77, v76
	v_pk_add_f32 v[174:175], v[76:77], v[170:171] neg_lo:[0,1] neg_hi:[0,1]
	v_mov_b32_e32 v173, v76
	v_pk_add_f32 v[76:77], v[174:175], v[172:173] neg_lo:[0,1] neg_hi:[0,1]
	ds_read_b128 v[240:243], v225 offset:128
	v_add_f32_e32 v77, v159, v77
	v_add_f32_e32 v76, v76, v77
	v_add_f32_e32 v77, v171, v76
	v_mul_f32_e32 v159, v179, v77
	v_mul_f32_e32 v170, v177, v159
	v_fma_f32 v172, v159, v177, -v170
	v_fmac_f32_e32 v172, v159, v178
	v_sub_f32_e32 v171, v171, v77
	v_add_f32_e32 v177, v76, v171
	v_add_f32_e32 v76, v170, v172
	v_sub_f32_e32 v171, v77, v76
	v_pk_add_f32 v[174:175], v[76:77], v[170:171] neg_lo:[0,1] neg_hi:[0,1]
	v_mov_b32_e32 v173, v76
	v_pk_add_f32 v[76:77], v[174:175], v[172:173] neg_lo:[0,1] neg_hi:[0,1]
	s_add_i32 s3, s3, s30
	v_add_f32_e32 v77, v177, v77
	v_add_f32_e32 v76, v76, v77
	v_add_f32_e32 v77, v169, v159
	v_add_f32_e32 v76, v171, v76
	v_sub_f32_e32 v169, v77, v169
	v_mul_f32_e32 v76, v179, v76
	v_sub_f32_e32 v159, v159, v169
	v_add_f32_e32 v169, v159, v76
	v_add_f32_e32 v170, v77, v169
	v_mul_f32_e32 v172, v170, v170
	v_fmamk_f32 v76, v172, 0x3e9b6dac, v221
	v_fmaak_f32 v159, v172, v76, 0x3f2aaada
	v_cvt_f32_i32_e32 v76, v176
	v_sub_f32_e32 v77, v170, v77
	v_sub_f32_e32 v77, v169, v77
	v_ldexp_f32 v169, v77, 1
	v_mul_f32_e32 v77, v170, v172
	v_pk_mul_f32 v[172:173], v[76:77], v[158:159]
	v_ldexp_f32 v171, v170, 1
	v_fma_f32 v170, v76, s90, -v172
	v_fmac_f32_e32 v170, 0xb102e308, v76
	v_pk_add_f32 v[76:77], v[172:173], v[170:171]
	v_mov_b32_e32 v174, v172
	v_sub_f32_e32 v159, v77, v171
	v_sub_f32_e32 v159, v173, v159
	v_add_f32_e32 v175, v169, v159
	v_pk_add_f32 v[172:173], v[76:77], v[172:173] neg_lo:[0,1] neg_hi:[0,1]
	v_pk_add_f32 v[176:177], v[76:77], v[174:175]
	v_mov_b32_e32 v171, v76
	v_mov_b32_e32 v173, v177
	v_pk_add_f32 v[178:179], v[170:171], v[172:173] neg_lo:[0,1] neg_hi:[0,1]
	v_pk_add_f32 v[170:171], v[170:171], v[172:173]
	v_mov_b32_e32 v182, v77
	v_pk_add_f32 v[172:173], v[170:171], v[76:77] op_sel:[1,0] op_sel_hi:[0,1] neg_lo:[0,1] neg_hi:[0,1]
	v_pk_add_f32 v[180:181], v[176:177], v[172:173] op_sel_hi:[1,0] neg_lo:[0,1] neg_hi:[0,1]
	v_mov_b32_e32 v176, v177
	v_mov_b32_e32 v177, v171
	v_mov_b32_e32 v183, v172
	v_pk_add_f32 v[172:173], v[176:177], v[182:183] neg_lo:[0,1] neg_hi:[0,1]
	v_mov_b32_e32 v174, v175
	v_mov_b32_e32 v175, v76
	v_pk_add_f32 v[76:77], v[174:175], v[172:173] neg_lo:[0,1] neg_hi:[0,1]
	v_mov_b32_e32 v180, v178
	v_pk_add_f32 v[172:173], v[180:181], v[76:77]
	v_mov_b32_e32 v179, v171
	v_pk_add_f32 v[174:175], v[172:173], v[172:173] op_sel:[0,1] op_sel_hi:[1,0]
	s_mov_b32 s16, 0
	v_pk_add_f32 v[170:171], v[170:171], v[174:175] op_sel:[1,0] op_sel_hi:[0,1]
	v_mov_b32_e32 v173, v170
	v_pk_add_f32 v[176:177], v[172:173], v[178:179] neg_lo:[0,1] neg_hi:[0,1]
	v_mov_b32_e32 v77, v174
	v_sub_f32_e32 v159, v172, v176
	v_pk_add_f32 v[76:77], v[76:77], v[176:177] neg_lo:[0,1] neg_hi:[0,1]
	v_sub_f32_e32 v159, v178, v159
	v_add_f32_e32 v76, v76, v159
	v_add_f32_e32 v76, v76, v77
	v_add_f32_e32 v76, v170, v76
	v_cndmask_b32_e64 v76, v224, v76, s[10:11]
	v_cndmask_b32_e64 v169, v76, v79, s[12:13]
	v_add_f32_e32 v76, -1.0, v162
	v_sub_f32_e32 v77, v76, v162
	v_add_f32_e32 v77, 1.0, v77
	v_sub_f32_e32 v76, v78, v76
	v_add_f32_e32 v79, v76, v77
	v_cvt_f64_f32_e32 v[76:77], v162
	v_frexp_exp_i32_f64_e32 v76, v[76:77]
	v_subbrev_co_u32_e64 v176, vcc, 0, v76, s[14:15]
	v_sub_u32_e32 v76, 0, v176
	v_ldexp_f32 v77, v162, v76
	v_ldexp_f32 v76, v79, v76
	v_add_f32_e32 v79, -1.0, v77
	v_add_f32_e32 v162, 1.0, v77
	v_add_f32_e32 v159, 1.0, v79
	v_add_f32_e32 v170, -1.0, v162
	v_sub_f32_e32 v159, v77, v159
	v_sub_f32_e32 v77, v77, v170
	v_add_f32_e32 v159, v76, v159
	v_add_f32_e32 v76, v76, v77
	v_add_f32_e32 v177, v162, v76
	v_rcp_f32_e32 v178, v177
	v_sub_f32_e32 v77, v162, v177
	v_add_f32_e32 v162, v76, v77
	v_add_f32_e32 v77, v79, v159
	v_sub_f32_e32 v76, v79, v77
	v_add_f32_e32 v79, v159, v76
	v_mul_f32_e32 v159, v77, v178
	v_mul_f32_e32 v170, v177, v159
	v_fma_f32 v172, v159, v177, -v170
	v_fmac_f32_e32 v172, v159, v162
	v_add_f32_e32 v76, v170, v172
	v_sub_f32_e32 v171, v77, v76
	v_pk_add_f32 v[174:175], v[76:77], v[170:171] neg_lo:[0,1] neg_hi:[0,1]
	v_mov_b32_e32 v173, v76
	v_pk_add_f32 v[76:77], v[174:175], v[172:173] neg_lo:[0,1] neg_hi:[0,1]
	ds_read_b128 v[236:239], v226 offset:64
	v_add_f32_e32 v77, v79, v77
	v_add_f32_e32 v76, v76, v77
	v_add_f32_e32 v77, v171, v76
	v_mul_f32_e32 v79, v178, v77
	v_mul_f32_e32 v170, v177, v79
	v_fma_f32 v172, v79, v177, -v170
	v_fmac_f32_e32 v172, v79, v162
	v_sub_f32_e32 v162, v171, v77
	v_add_f32_e32 v162, v76, v162
	v_add_f32_e32 v76, v170, v172
	v_sub_f32_e32 v171, v77, v76
	v_pk_add_f32 v[174:175], v[76:77], v[170:171] neg_lo:[0,1] neg_hi:[0,1]
	v_mov_b32_e32 v173, v76
	v_pk_add_f32 v[76:77], v[174:175], v[172:173] neg_lo:[0,1] neg_hi:[0,1]
	s_mov_b32 s58, 0
	v_add_f32_e32 v77, v162, v77
	v_add_f32_e32 v76, v76, v77
	v_add_f32_e32 v77, v159, v79
	v_add_f32_e32 v76, v171, v76
	v_sub_f32_e32 v159, v77, v159
	v_mul_f32_e32 v76, v178, v76
	v_sub_f32_e32 v79, v79, v159
	v_add_f32_e32 v79, v79, v76
	v_add_f32_e32 v162, v77, v79
	v_mul_f32_e32 v170, v162, v162
	v_fmamk_f32 v76, v170, 0x3e9b6dac, v221
	v_fmaak_f32 v159, v170, v76, 0x3f2aaada
	v_cvt_f32_i32_e32 v76, v176
	v_sub_f32_e32 v77, v162, v77
	v_sub_f32_e32 v77, v79, v77
	v_ldexp_f32 v79, v77, 1
	v_mul_f32_e32 v77, v162, v170
	v_pk_mul_f32 v[172:173], v[76:77], v[158:159]
	v_ldexp_f32 v171, v162, 1
	v_fma_f32 v170, v76, s90, -v172
	v_fmac_f32_e32 v170, 0xb102e308, v76
	v_pk_add_f32 v[76:77], v[172:173], v[170:171]
	v_mov_b32_e32 v174, v172
	v_sub_f32_e32 v159, v77, v171
	v_sub_f32_e32 v159, v173, v159
	v_add_f32_e32 v175, v79, v159
	v_pk_add_f32 v[172:173], v[76:77], v[172:173] neg_lo:[0,1] neg_hi:[0,1]
	v_pk_add_f32 v[176:177], v[76:77], v[174:175]
	v_mov_b32_e32 v171, v76
	v_mov_b32_e32 v173, v177
	v_pk_add_f32 v[178:179], v[170:171], v[172:173] neg_lo:[0,1] neg_hi:[0,1]
	v_pk_add_f32 v[170:171], v[170:171], v[172:173]
	v_mov_b32_e32 v182, v77
	v_pk_add_f32 v[172:173], v[170:171], v[76:77] op_sel:[1,0] op_sel_hi:[0,1] neg_lo:[0,1] neg_hi:[0,1]
	v_pk_add_f32 v[180:181], v[176:177], v[172:173] op_sel_hi:[1,0] neg_lo:[0,1] neg_hi:[0,1]
	v_mov_b32_e32 v176, v177
	v_mov_b32_e32 v177, v171
	v_mov_b32_e32 v183, v172
	v_pk_add_f32 v[172:173], v[176:177], v[182:183] neg_lo:[0,1] neg_hi:[0,1]
	v_mov_b32_e32 v174, v175
	v_mov_b32_e32 v175, v76
	v_pk_add_f32 v[76:77], v[174:175], v[172:173] neg_lo:[0,1] neg_hi:[0,1]
	v_mov_b32_e32 v180, v178
	v_pk_add_f32 v[172:173], v[180:181], v[76:77]
	v_mov_b32_e32 v179, v171
	v_pk_add_f32 v[174:175], v[172:173], v[172:173] op_sel:[0,1] op_sel_hi:[1,0]
	v_mul_f32_e32 v159, 0xbfb8aa3b, v169
	v_pk_add_f32 v[170:171], v[170:171], v[174:175] op_sel:[1,0] op_sel_hi:[0,1]
	v_mov_b32_e32 v173, v170
	v_pk_add_f32 v[176:177], v[172:173], v[178:179] neg_lo:[0,1] neg_hi:[0,1]
	v_mov_b32_e32 v77, v174
	v_sub_f32_e32 v79, v172, v176
	v_pk_add_f32 v[76:77], v[76:77], v[176:177] neg_lo:[0,1] neg_hi:[0,1]
	v_sub_f32_e32 v79, v178, v79
	v_add_f32_e32 v76, v76, v79
	v_add_f32_e32 v76, v76, v77
	v_add_f32_e32 v76, v170, v76
	v_cndmask_b32_e64 v76, v224, v76, s[6:7]
	v_cndmask_b32_e64 v162, v76, v78, s[8:9]
	ds_read_b128 v[76:79], v225
	ds_read_b128 v[174:177], v225 offset:64
	ds_read_b128 v[170:173], v226
	s_and_b32 s6, s92, 0x180
	s_add_i32 s6, s6, s68
	v_mul_f32_e32 v235, 0xbfb8aa3b, v162
	v_or_b32_e32 v162, s6, v193
	v_add_u32_e32 v169, 1, v162
	v_sub_u32_e32 v162, 0x200, v162
	v_cvt_f32_i32_e32 v162, v162
	v_cvt_f32_i32_e32 v169, v169
	s_waitcnt lgkmcnt(0)
	v_mfma_f32_16x16x32_bf16 v[76:79], v[76:79], v[0:3], 0
	s_and_b32 s7, s69, 0x180
	v_mul_f32_e32 v162, v235, v162
	v_mul_f32_e32 v169, v159, v169
	v_mfma_f32_16x16x32_bf16 v[170:173], v[170:173], v[0:3], 0
	v_exp_f32_e32 v180, v162
	v_exp_f32_e32 v178, v169
	v_add_u32_e32 v231, s7, v142
	v_mfma_f32_16x16x32_bf16 v[76:79], v[174:177], v[4:7], v[76:79]
	ds_read_b128 v[174:177], v226 offset:128
	v_pk_mul_f32 v[68:69], v[180:181], v[68:69] op_sel_hi:[0,1]
	v_pk_mul_f32 v[182:183], v[180:181], v[70:71] op_sel_hi:[0,1]
	v_mfma_f32_16x16x32_bf16 v[170:173], v[236:239], v[4:7], v[170:173]
	ds_read_b128 v[236:239], v225 offset:192
	v_pk_mul_f32 v[92:93], v[180:181], v[92:93] op_sel_hi:[0,1]
	v_pk_fma_f32 v[72:73], v[178:179], v[72:73], v[92:93] op_sel_hi:[0,1,1]
	v_mfma_f32_16x16x32_bf16 v[240:243], v[240:243], v[8:11], v[76:79]
	v_mul_f32_e64 v84, v180, v84
	v_mul_f32_e64 v85, v180, v85
	v_pk_mul_f32 v[96:97], v[180:181], v[96:97] op_sel_hi:[0,1]
	v_pk_fma_f32 v[88:89], v[178:179], v[88:89], v[96:97] op_sel_hi:[0,1,1]
	v_pk_fma_f32 v[76:77], v[178:179], v[64:65], v[68:69] op_sel_hi:[0,1,1]
	ds_read_b128 v[68:71], v226 offset:192
	v_pk_fma_f32 v[78:79], v[178:179], v[66:67], v[182:183] op_sel_hi:[0,1,1]
	ds_read_b128 v[64:67], v225 offset:256
	s_waitcnt lgkmcnt(3)
	v_mfma_f32_16x16x32_bf16 v[170:173], v[174:177], v[8:11], v[170:173]
	v_mul_f32_e64 v182, v180, v94
	v_mul_f32_e64 v183, v180, v95
	ds_read_b128 v[92:95], v226 offset:256
	v_pk_mul_f32 v[54:55], v[180:181], v[54:55] op_sel_hi:[0,1]
	s_waitcnt lgkmcnt(3)
	v_mfma_f32_16x16x32_bf16 v[174:177], v[236:239], v[12:15], v[240:243]
	ds_read_b128 v[236:239], v225 offset:320
	v_pk_mul_f32 v[52:53], v[180:181], v[52:53] op_sel_hi:[0,1]
	v_pk_fma_f32 v[52:53], v[178:179], v[48:49], v[52:53] op_sel_hi:[0,1,1]
	s_waitcnt lgkmcnt(3)
	v_mfma_f32_16x16x32_bf16 v[170:173], v[68:71], v[12:15], v[170:173]
	v_mul_f32_e64 v70, v180, v122
	v_mul_f32_e64 v71, v180, v123
	v_pk_mul_f32 v[68:69], v[180:181], v[120:121] op_sel_hi:[0,1]
	ds_read_b128 v[120:123], v226 offset:320
	s_waitcnt lgkmcnt(3)
	v_mfma_f32_16x16x32_bf16 v[64:67], v[64:67], v[16:19], v[174:177]
	v_fma_f32 v68, v178, v116, v68
	v_fma_f32 v69, v178, v117, v69
	v_pk_fma_f32 v[70:71], v[178:179], v[118:119], v[70:71] op_sel_hi:[0,1,1]
	ds_read_b128 v[116:119], v225 offset:384
	s_waitcnt lgkmcnt(3)
	v_mfma_f32_16x16x32_bf16 v[92:95], v[92:95], v[16:19], v[170:173]
	v_mul_f32_e64 v174, v180, v130
	v_mul_f32_e64 v175, v180, v131
	v_pk_fma_f32 v[54:55], v[178:179], v[50:51], v[54:55] op_sel_hi:[0,1,1]
	v_pk_mul_f32 v[50:51], v[180:181], v[62:63] op_sel_hi:[0,1]
	s_waitcnt lgkmcnt(2)
	v_mfma_f32_16x16x32_bf16 v[170:173], v[236:239], v[20:23], v[64:67]
	v_mul_f32_e64 v48, v180, v60
	v_mul_f32_e64 v49, v180, v61
	v_pk_fma_f32 v[48:49], v[178:179], v[56:57], v[48:49] op_sel_hi:[0,1,1]
	v_pk_fma_f32 v[50:51], v[178:179], v[58:59], v[50:51] op_sel_hi:[0,1,1]
	v_pk_mul_f32 v[64:65], v[180:181], v[128:129] op_sel_hi:[0,1]
	ds_read_b128 v[128:131], v226 offset:384
	v_pk_fma_f32 v[64:65], v[178:179], v[124:125], v[64:65] op_sel_hi:[0,1,1]
	s_waitcnt lgkmcnt(2)
	v_mfma_f32_16x16x32_bf16 v[120:123], v[120:123], v[20:23], v[92:95]
	v_fma_f32 v66, v178, v126, v174
	v_fma_f32 v67, v178, v127, v175
	ds_read_b128 v[124:127], v225 offset:448
	v_mul_f32_e64 v60, v159, -v196
	v_pk_mul_f32 v[94:95], v[180:181], v[86:87] op_sel_hi:[0,1]
	v_pk_fma_f32 v[92:93], v[178:179], v[80:81], v[84:85] op_sel_hi:[0,1,1]
	ds_read_b128 v[84:87], v226 offset:448
	s_waitcnt lgkmcnt(3)
	v_mfma_f32_16x16x32_bf16 v[116:119], v[116:119], v[24:27], v[170:173]
	v_fma_f32 v94, v178, v82, v94
	v_fma_f32 v95, v178, v83, v95
	ds_read_b128 v[80:83], v168
	v_add_u32_e32 v237, s7, v220
	s_waitcnt lgkmcnt(3)
	v_mfma_f32_16x16x32_bf16 v[120:123], v[128:131], v[24:27], v[120:123]
	v_mul_f32_e64 v128, v180, v98
	v_mul_f32_e64 v129, v180, v99
	ds_read_b128 v[96:99], v167
	v_pk_fma_f32 v[90:91], v[178:179], v[90:91], v[128:129] op_sel_hi:[0,1,1]
	s_waitcnt lgkmcnt(3)
	v_mfma_f32_16x16x32_bf16 v[116:119], v[124:127], v[28:31], v[116:119]
	ds_read_b128 v[124:127], v227 offset:64
	v_pk_mul_f32 v[168:169], v[180:181], v[114:115] op_sel_hi:[0,1]
	s_lshl_b32 s7, s69, 11
	s_waitcnt lgkmcnt(3)
	v_mfma_f32_16x16x32_bf16 v[120:123], v[84:87], v[28:31], v[120:123]
	v_mul_f32_e64 v86, v180, v106
	v_mul_f32_e64 v87, v180, v107
	v_pk_mul_f32 v[84:85], v[180:181], v[104:105] op_sel_hi:[0,1]
	ds_read_b128 v[104:107], v228 offset:64
	s_waitcnt lgkmcnt(3)
	v_mfma_f32_16x16x32_bf16 v[80:83], v[80:83], v[0:3], 0
	v_fma_f32 v84, v178, v100, v84
	v_fma_f32 v85, v178, v101, v85
	v_pk_fma_f32 v[86:87], v[178:179], v[102:103], v[86:87] op_sel_hi:[0,1,1]
	ds_read_b128 v[100:103], v227 offset:128
	s_waitcnt lgkmcnt(3)
	v_mfma_f32_16x16x32_bf16 v[96:99], v[96:99], v[0:3], 0
	s_and_b32 s10, s7, 0x700000
	s_lshl_b32 s7, s73, 1
	s_and_b32 s11, s7, 0x600
	s_waitcnt lgkmcnt(2)
	v_mfma_f32_16x16x32_bf16 v[124:127], v[124:127], v[4:7], v[80:83]
	s_ashr_i32 s17, s6, 6
	s_cmpk_lt_i32 s3, 0x200
	s_cselect_b64 s[8:9], -1, 0
	v_pk_mul_f32 v[80:81], v[180:181], v[112:113] op_sel_hi:[0,1]
	ds_read_b128 v[112:115], v228 offset:128
	ds_read_b128 v[128:131], v227 offset:448
	s_waitcnt lgkmcnt(3)
	v_mfma_f32_16x16x32_bf16 v[96:99], v[104:107], v[4:7], v[96:99]
	ds_read_b128 v[104:107], v227 offset:192
	v_pk_fma_f32 v[80:81], v[178:179], v[108:109], v[80:81] op_sel_hi:[0,1,1]
	v_pk_fma_f32 v[82:83], v[178:179], v[110:111], v[168:169] op_sel_hi:[0,1,1]
	s_waitcnt lgkmcnt(3)
	v_mfma_f32_16x16x32_bf16 v[108:111], v[100:103], v[8:11], v[124:127]
	v_mul_f32_e64 v102, v180, v38
	v_mul_f32_e64 v103, v180, v39
	v_pk_mul_f32 v[100:101], v[180:181], v[36:37] op_sel_hi:[0,1]
	ds_read_b128 v[36:39], v228 offset:192
	v_pk_fma_f32 v[100:101], v[178:179], v[32:33], v[100:101] op_sel_hi:[0,1,1]
	v_pk_fma_f32 v[102:103], v[178:179], v[34:35], v[102:103] op_sel_hi:[0,1,1]
	ds_read_b128 v[32:35], v227 offset:256
	s_waitcnt lgkmcnt(2)
	v_mfma_f32_16x16x32_bf16 v[104:107], v[104:107], v[12:15], v[108:111]
	ds_read_b128 v[56:59], v164
	s_cmpk_gt_i32 s3, 0x1ff
	s_cselect_b64 s[6:7], -1, 0
	v_pk_mul_f32 v[108:109], v[180:181], v[46:47] op_sel_hi:[0,1]
	v_pk_mul_f32 v[110:111], v[180:181], v[44:45] op_sel_hi:[0,1]
	ds_read_b128 v[44:47], v228 offset:256
	v_mfma_f32_16x16x32_bf16 v[96:99], v[112:115], v[8:11], v[96:99]
	v_exp_f32_e32 v112, v60
	ds_read_b128 v[60:63], v232 offset:64
	s_ashr_i32 s13, s3, 1
	s_waitcnt lgkmcnt(4)
	v_mfma_f32_16x16x32_bf16 v[36:39], v[36:39], v[12:15], v[96:99]
	s_bfe_u32 s12, s3, 0x30002
	s_and_b32 s13, s13, -16
	s_or_b32 s12, s13, s12
	s_nop 0
	v_pk_fma_f32 v[96:97], v[178:179], v[40:41], v[110:111] op_sel_hi:[0,1,1]
	v_pk_fma_f32 v[98:99], v[178:179], v[42:43], v[108:109] op_sel_hi:[0,1,1]
	ds_read_b128 v[40:43], v227 offset:320
	s_waitcnt lgkmcnt(2)
	v_mfma_f32_16x16x32_bf16 v[36:39], v[44:47], v[16:19], v[36:39]
	ds_read_b128 v[44:47], v227 offset:384
	s_ashr_i32 s13, s12, 31
	s_lshl_b64 s[14:15], s[12:13], 17
	v_mfma_f32_16x16x32_bf16 v[32:35], v[32:35], v[16:19], v[104:107]
	s_add_u32 s18, s46, s14
	s_addc_u32 s19, s47, s15
	s_or_b32 s12, s12, 8
	ds_read_b128 v[104:107], v228 offset:320
	s_waitcnt lgkmcnt(2)
	v_mfma_f32_16x16x32_bf16 v[32:35], v[40:43], v[20:23], v[32:35]
	ds_read_b128 v[40:43], v228 offset:384
	s_ashr_i32 s13, s12, 31
	s_lshl_b64 s[12:13], s[12:13], 17
	s_waitcnt lgkmcnt(2)
	v_mfma_f32_16x16x32_bf16 v[32:35], v[44:47], v[24:27], v[32:35]
	ds_read_b128 v[44:47], v228 offset:448
	v_mul_f32_e32 v125, v235, v198
	v_mul_f32_e32 v167, v235, v204
	s_waitcnt lgkmcnt(2)
	v_mfma_f32_16x16x32_bf16 v[36:39], v[104:107], v[20:23], v[36:39]
	v_mul_f32_e32 v104, v235, v196
	v_exp_f32_e32 v114, v104
	ds_read_b128 v[104:107], v229 offset:128
	s_waitcnt lgkmcnt(2)
	v_mfma_f32_16x16x32_bf16 v[36:39], v[40:43], v[24:27], v[36:39]
	ds_read_b128 v[40:43], v166
	s_add_u32 s54, s46, s12
	v_pk_fma_f32 v[74:75], v[178:179], v[74:75], v[182:183] op_sel_hi:[0,1,1]
	s_waitcnt lgkmcnt(2)
	v_mfma_f32_16x16x32_bf16 v[36:39], v[44:47], v[28:31], v[36:39]
	ds_read_b128 v[44:47], v229 offset:64
	v_mul_f32_e64 v113, v159, -v197
	v_mul_f32_e32 v115, v235, v197
	s_waitcnt lgkmcnt(1)
	v_mfma_f32_16x16x32_bf16 v[40:43], v[40:43], v[0:3], 0
	v_mul_f32_e64 v124, v159, -v198
	v_exp_f32_e32 v126, v125
	v_mul_f32_e64 v125, v159, -v199
	v_mfma_f32_16x16x32_bf16 v[56:59], v[56:59], v[0:3], 0
	v_mul_f32_e32 v127, v235, v199
	v_exp_f32_e32 v168, v167
	v_mul_f32_e64 v167, v159, -v205
	s_waitcnt lgkmcnt(0)
	v_mfma_f32_16x16x32_bf16 v[40:43], v[44:47], v[4:7], v[40:43]
	ds_read_b128 v[44:47], v232 offset:128
	ds_read_b128 v[108:111], v229 offset:448
	ds_read_b128 v[170:173], v233 offset:128
	v_mul_f32_e32 v169, v235, v205
	v_mfma_f32_16x16x32_bf16 v[56:59], v[60:63], v[4:7], v[56:59]
	ds_read_b128 v[60:63], v229 offset:192
	v_mul_f32_e64 v179, v159, -v211
	s_addc_u32 s55, s47, s13
	v_mfma_f32_16x16x32_bf16 v[40:43], v[104:107], v[8:11], v[40:43]
	ds_read_b128 v[104:107], v232 offset:192
	s_lshl_b64 s[12:13], s[52:53], 23
	v_exp_f32_e32 v113, v113
	s_waitcnt lgkmcnt(4)
	v_mfma_f32_16x16x32_bf16 v[44:47], v[44:47], v[8:11], v[56:59]
	v_exp_f32_e32 v115, v115
	v_exp_f32_e32 v124, v124
	v_exp_f32_e32 v125, v125
	ds_read_b128 v[56:59], v229 offset:256
	s_waitcnt lgkmcnt(2)
	v_mfma_f32_16x16x32_bf16 v[40:43], v[60:63], v[12:15], v[40:43]
	ds_read_b128 v[60:63], v232 offset:256
	v_exp_f32_e32 v127, v127
	v_exp_f32_e32 v167, v167
	s_waitcnt lgkmcnt(2)
	v_mfma_f32_16x16x32_bf16 v[44:47], v[104:107], v[12:15], v[44:47]
	ds_read_b128 v[104:107], v229 offset:320
	v_exp_f32_e32 v169, v169
	v_pk_mul_f32 v[36:37], v[180:181], v[36:37] op_sel_hi:[0,1]
	s_waitcnt lgkmcnt(1)
	v_mfma_f32_16x16x32_bf16 v[44:47], v[60:63], v[16:19], v[44:47]
	ds_read_b128 v[60:63], v229 offset:384
	s_or_b32 s10, s12, s10
	v_pk_mul_f32 v[38:39], v[180:181], v[38:39] op_sel_hi:[0,1]
	v_mfma_f32_16x16x32_bf16 v[40:43], v[56:59], v[16:19], v[40:43]
	ds_read_b128 v[56:59], v232 offset:320
	s_or_b32 s10, s10, s11
	s_add_u32 s52, s71, s10
	s_waitcnt lgkmcnt(2)
	v_mfma_f32_16x16x32_bf16 v[40:43], v[104:107], v[20:23], v[40:43]
	ds_read_b128 v[104:107], v232 offset:384
	v_sub_u32_e32 v236, 0, v231
	s_addc_u32 s53, s72, s13
	s_waitcnt lgkmcnt(2)
	v_mfma_f32_16x16x32_bf16 v[40:43], v[60:63], v[24:27], v[40:43]
	v_mul_f32_e32 v60, v235, v202
	v_exp_f32_e32 v164, v60
	ds_read_b128 v[60:63], v163
	s_waitcnt lgkmcnt(2)
	v_mfma_f32_16x16x32_bf16 v[44:47], v[56:59], v[20:23], v[44:47]
	v_mul_f32_e32 v56, v235, v201
	v_mfma_f32_16x16x32_bf16 v[32:35], v[128:131], v[28:31], v[32:35]
	v_exp_f32_e32 v131, v56
	v_mul_f32_e64 v56, v159, -v202
	v_exp_f32_e32 v162, v56
	ds_read_b128 v[56:59], v232 offset:448
	s_waitcnt lgkmcnt(2)
	v_mfma_f32_16x16x32_bf16 v[44:47], v[104:107], v[24:27], v[44:47]
	v_mul_f32_e32 v129, v235, v200
	v_mul_f32_e64 v128, v159, -v200
	v_exp_f32_e32 v130, v129
	v_mfma_f32_16x16x32_bf16 v[104:107], v[108:111], v[28:31], v[40:43]
	v_mul_f32_e64 v108, v159, -v204
	v_exp_f32_e32 v166, v108
	ds_read_b128 v[108:111], v234 offset:64
	v_mul_f32_e64 v40, v159, -v203
	v_exp_f32_e32 v163, v40
	ds_read_b128 v[40:43], v165
	s_waitcnt lgkmcnt(2)
	v_mfma_f32_16x16x32_bf16 v[56:59], v[56:59], v[28:31], v[44:47]
	v_mul_f32_e64 v129, v159, -v201
	v_exp_f32_e32 v128, v128
	v_exp_f32_e32 v129, v129
	v_mul_f32_e32 v44, v235, v203
	v_exp_f32_e32 v165, v44
	ds_read_b128 v[44:47], v233 offset:64
	v_mfma_f32_16x16x32_bf16 v[60:63], v[60:63], v[0:3], 0
	s_waitcnt lgkmcnt(1)
	v_mfma_f32_16x16x32_bf16 v[40:43], v[40:43], v[0:3], 0
	s_waitcnt lgkmcnt(0)
	v_mfma_f32_16x16x32_bf16 v[44:47], v[44:47], v[4:7], v[60:63]
	s_nop 4
	ds_read_b128 v[60:63], v234 offset:128
	ds_read_b128 v[240:243], v233 offset:448
	ds_read_b128 v[174:177], v234 offset:192
	ds_read_b128 v[244:247], v233 offset:320
	v_mfma_f32_16x16x32_bf16 v[40:43], v[108:111], v[4:7], v[40:43]
	ds_read_b128 v[108:111], v233 offset:192
	s_waitcnt lgkmcnt(4)
	v_mfma_f32_16x16x32_bf16 v[40:43], v[60:63], v[8:11], v[40:43]
	ds_read_b128 v[60:63], v233 offset:256
	v_mfma_f32_16x16x32_bf16 v[44:47], v[170:173], v[8:11], v[44:47]
	v_mul_f32_e32 v171, v235, v206
	v_mul_f32_e64 v170, v159, -v206
	v_exp_f32_e32 v172, v171
	s_waitcnt lgkmcnt(1)
	v_mfma_f32_16x16x32_bf16 v[44:47], v[108:111], v[12:15], v[44:47]
	ds_read_b128 v[108:111], v234 offset:256
	v_mul_f32_e64 v171, v159, -v207
	v_mul_f32_e32 v173, v235, v207
	s_waitcnt lgkmcnt(1)
	v_mfma_f32_16x16x32_bf16 v[44:47], v[60:63], v[16:19], v[44:47]
	ds_read_b128 v[60:63], v234 offset:320
	v_exp_f32_e32 v170, v170
	v_exp_f32_e32 v171, v171
	v_mfma_f32_16x16x32_bf16 v[40:43], v[174:177], v[12:15], v[40:43]
	v_mul_f32_e32 v175, v235, v208
	v_mul_f32_e64 v174, v159, -v208
	v_exp_f32_e32 v176, v175
	s_waitcnt lgkmcnt(1)
	v_mfma_f32_16x16x32_bf16 v[40:43], v[108:111], v[16:19], v[40:43]
	ds_read_b128 v[108:111], v233 offset:384
	v_mul_f32_e64 v175, v159, -v209
	v_exp_f32_e32 v173, v173
	v_mfma_f32_16x16x32_bf16 v[44:47], v[244:247], v[20:23], v[44:47]
	ds_read_b128 v[244:247], v234 offset:384
	v_exp_f32_e32 v174, v174
	v_exp_f32_e32 v175, v175
	s_waitcnt lgkmcnt(2)
	v_mfma_f32_16x16x32_bf16 v[40:43], v[60:63], v[20:23], v[40:43]
	v_mul_f32_e32 v60, v235, v209
	v_exp_f32_e32 v177, v60
	v_mul_f32_e64 v60, v159, -v210
	v_exp_f32_e32 v238, v60
	ds_read_b128 v[60:63], v234 offset:448
	s_waitcnt lgkmcnt(1)
	v_mfma_f32_16x16x32_bf16 v[40:43], v[244:247], v[24:27], v[40:43]
	s_waitcnt vmcnt(0)
	s_waitcnt vmcnt(0)
	s_waitcnt lgkmcnt(0)
	s_barrier
	v_mfma_f32_16x16x32_bf16 v[44:47], v[108:111], v[24:27], v[44:47]
	v_mul_f32_e32 v108, v235, v210
	v_exp_f32_e32 v239, v108
	v_mfma_f32_16x16x32_bf16 v[60:63], v[60:63], v[28:31], v[40:43]
	v_mfma_f32_16x16x32_bf16 v[108:111], v[240:243], v[28:31], v[44:47]
	v_exp_f32_e32 v240, v179
	s_nop 0
	v_pk_mul_f32 v[40:41], v[180:181], v[122:123] op_sel_hi:[0,1]
	v_pk_mul_f32 v[42:43], v[180:181], v[120:121] op_sel_hi:[0,1]
	v_mul_f32_e32 v44, v235, v211
	v_exp_f32_e32 v241, v44
	v_pk_fma_f32 v[46:47], v[178:179], v[118:119], v[40:41] op_sel_hi:[0,1,1]
	v_pk_fma_f32 v[40:41], v[178:179], v[32:33], v[36:37] op_sel_hi:[0,1,1]
	v_pk_mul_f32 v[32:33], v[180:181], v[58:59] op_sel_hi:[0,1]
	v_pk_fma_f32 v[44:45], v[178:179], v[116:117], v[42:43] op_sel_hi:[0,1,1]
	v_pk_fma_f32 v[42:43], v[178:179], v[34:35], v[38:39] op_sel_hi:[0,1,1]
	v_pk_mul_f32 v[34:35], v[180:181], v[56:57] op_sel_hi:[0,1]
	v_pk_fma_f32 v[38:39], v[178:179], v[106:107], v[32:33] op_sel_hi:[0,1,1]
	v_pk_mul_f32 v[32:33], v[180:181], v[62:63] op_sel_hi:[0,1]
	v_pk_mul_f32 v[56:57], v[180:181], v[60:61] op_sel_hi:[0,1]
	v_pk_fma_f32 v[36:37], v[178:179], v[104:105], v[34:35] op_sel_hi:[0,1,1]
	v_pk_fma_f32 v[34:35], v[178:179], v[110:111], v[32:33] op_sel_hi:[0,1,1]
	v_pk_fma_f32 v[32:33], v[178:179], v[108:109], v[56:57] op_sel_hi:[0,1,1]
	s_branch .LBB0_1094

.LBB0_1097:
	s_bitcmp1_b32 s58, 0
	s_cselect_b32 s10, 0x11000, 0
	s_add_i32 s12, s10, 0
	v_add3_u32 v178, s12, v194, v212
	ds_read_b128 v[56:59], v178
	ds_read_b128 v[60:63], v178 offset:64
	ds_read_b128 v[104:107], v178 offset:8704
	ds_read_b128 v[108:111], v178 offset:8768
	ds_read_b128 v[116:119], v178 offset:8832
	ds_read_b128 v[120:123], v178 offset:26240
	s_waitcnt lgkmcnt(0)
	v_mfma_f32_16x16x32_bf16 v[56:59], v[56:59], v[0:3], 0
	s_mov_b64 s[10:11], -1
	s_cmp_ge_i32 s58, s17
	ds_read_b128 v[244:247], v178 offset:26560
	v_mfma_f32_16x16x32_bf16 v[104:107], v[104:107], v[0:3], 0
	v_mfma_f32_16x16x32_bf16 v[56:59], v[60:63], v[4:7], v[56:59]
	ds_read_b128 v[60:63], v178 offset:128
	v_mfma_f32_16x16x32_bf16 v[104:107], v[108:111], v[4:7], v[104:107]
	ds_read_b128 v[108:111], v178 offset:192
	s_waitcnt lgkmcnt(1)
	v_mfma_f32_16x16x32_bf16 v[56:59], v[60:63], v[8:11], v[56:59]
	ds_read_b128 v[60:63], v178 offset:256
	s_waitcnt lgkmcnt(1)
	v_mfma_f32_16x16x32_bf16 v[56:59], v[108:111], v[12:15], v[56:59]
	ds_read_b128 v[108:111], v178 offset:320
	s_waitcnt lgkmcnt(1)
	v_mfma_f32_16x16x32_bf16 v[56:59], v[60:63], v[16:19], v[56:59]
	ds_read_b128 v[60:63], v178 offset:384
	s_waitcnt lgkmcnt(1)
	v_mfma_f32_16x16x32_bf16 v[56:59], v[108:111], v[20:23], v[56:59]
	ds_read_b128 v[108:111], v178 offset:448
	s_waitcnt lgkmcnt(1)
	v_mfma_f32_16x16x32_bf16 v[56:59], v[60:63], v[24:27], v[56:59]
	s_waitcnt lgkmcnt(0)
	v_mfma_f32_16x16x32_bf16 v[60:63], v[108:111], v[28:31], v[56:59]
	ds_read_b128 v[108:111], v178 offset:8960
	s_nop 5
	ds_read_b128 v[56:59], v178 offset:8896
	v_mfma_f32_16x16x32_bf16 v[104:107], v[116:119], v[8:11], v[104:107]
	ds_read_b128 v[116:119], v178 offset:17536
	s_waitcnt lgkmcnt(1)
	v_mfma_f32_16x16x32_bf16 v[56:59], v[56:59], v[12:15], v[104:107]
	s_nop 4
	ds_read_b128 v[104:107], v178 offset:9024
	v_mfma_f32_16x16x32_bf16 v[56:59], v[108:111], v[16:19], v[56:59]
	ds_read_b128 v[108:111], v178 offset:9088
	s_waitcnt lgkmcnt(1)
	v_mfma_f32_16x16x32_bf16 v[56:59], v[104:107], v[20:23], v[56:59]
	ds_read_b128 v[104:107], v178 offset:9152
	s_waitcnt lgkmcnt(1)
	v_mfma_f32_16x16x32_bf16 v[56:59], v[108:111], v[24:27], v[56:59]
	ds_read_b128 v[108:111], v178 offset:17408
	s_waitcnt lgkmcnt(1)
	v_mfma_f32_16x16x32_bf16 v[104:107], v[104:107], v[28:31], v[56:59]
	s_nop 4
	ds_read_b128 v[56:59], v178 offset:17472
	s_waitcnt lgkmcnt(1)
	v_mfma_f32_16x16x32_bf16 v[108:111], v[108:111], v[0:3], 0
	s_waitcnt lgkmcnt(0)
	v_mfma_f32_16x16x32_bf16 v[56:59], v[56:59], v[4:7], v[108:111]
	s_nop 5
	ds_read_b128 v[108:111], v178 offset:17600
	v_mfma_f32_16x16x32_bf16 v[56:59], v[116:119], v[8:11], v[56:59]
	ds_read_b128 v[116:119], v178 offset:17664
	s_waitcnt lgkmcnt(1)
	v_mfma_f32_16x16x32_bf16 v[56:59], v[108:111], v[12:15], v[56:59]
	ds_read_b128 v[108:111], v178 offset:17728
	s_waitcnt lgkmcnt(1)
	v_mfma_f32_16x16x32_bf16 v[56:59], v[116:119], v[16:19], v[56:59]
	ds_read_b128 v[116:119], v178 offset:17792
	s_waitcnt lgkmcnt(1)
	v_mfma_f32_16x16x32_bf16 v[56:59], v[108:111], v[20:23], v[56:59]
	ds_read_b128 v[108:111], v178 offset:17856
	s_waitcnt lgkmcnt(1)
	v_mfma_f32_16x16x32_bf16 v[56:59], v[116:119], v[24:27], v[56:59]
	ds_read_b128 v[116:119], v178 offset:26112
	s_waitcnt lgkmcnt(1)
	v_mfma_f32_16x16x32_bf16 v[108:111], v[108:111], v[28:31], v[56:59]
	s_nop 4
	ds_read_b128 v[56:59], v178 offset:26176
	s_waitcnt lgkmcnt(1)
	v_mfma_f32_16x16x32_bf16 v[116:119], v[116:119], v[0:3], 0
	s_waitcnt lgkmcnt(0)
	v_mfma_f32_16x16x32_bf16 v[56:59], v[56:59], v[4:7], v[116:119]
	s_nop 5
	ds_read_b128 v[116:119], v178 offset:26304
	v_mfma_f32_16x16x32_bf16 v[56:59], v[120:123], v[8:11], v[56:59]
	ds_read_b128 v[120:123], v178 offset:26368
	s_waitcnt lgkmcnt(1)
	v_mfma_f32_16x16x32_bf16 v[56:59], v[116:119], v[12:15], v[56:59]
	ds_read_b128 v[116:119], v178 offset:26432
	s_waitcnt lgkmcnt(1)
	v_mfma_f32_16x16x32_bf16 v[56:59], v[120:123], v[16:19], v[56:59]
	ds_read_b128 v[120:123], v178 offset:26496
	s_waitcnt lgkmcnt(1)
	v_mfma_f32_16x16x32_bf16 v[56:59], v[116:119], v[20:23], v[56:59]
	s_waitcnt lgkmcnt(0)
	v_mfma_f32_16x16x32_bf16 v[56:59], v[120:123], v[24:27], v[56:59]
	v_mfma_f32_16x16x32_bf16 v[56:59], v[244:247], v[28:31], v[56:59]
	s_cbranch_scc0 .LBB0_1103
	s_cmp_gt_i32 s58, s17
	s_cbranch_scc1 .LBB0_1100
	v_add_u32_e32 v242, s16, v237
	v_sub_u32_e32 v116, 0, v242
	v_max_i32_e32 v116, v242, v116
	v_cvt_f32_u32_e32 v116, v116
	v_cmp_gt_i32_e32 vcc, 0, v242
	v_add_u32_e32 v118, -1, v242
	v_sub_u32_e32 v119, 2, v242
	v_cndmask_b32_e32 v117, v159, v235, vcc
	v_mul_f32_e32 v116, v117, v116
	v_sub_u32_e32 v117, 1, v242
	v_max_i32_e32 v117, v118, v117
	v_cvt_f32_u32_e32 v117, v117
	v_cmp_gt_i32_e32 vcc, 0, v118
	v_exp_f32_e32 v116, v116
	v_sub_u32_e32 v178, 35, v242
	v_cndmask_b32_e32 v118, v159, v235, vcc
	v_mul_f32_e32 v117, v118, v117
	v_exp_f32_e32 v117, v117
	v_add_u32_e32 v118, -2, v242
	v_max_i32_e32 v119, v118, v119
	v_cmp_gt_i32_e32 vcc, 0, v118
	v_pk_mul_f32 v[120:121], v[116:117], v[60:61]
	v_add_u32_e32 v117, -3, v242
	v_sub_u32_e32 v118, 3, v242
	v_max_i32_e32 v118, v117, v118
	v_cvt_f32_u32_e32 v119, v119
	v_cvt_f32_u32_e32 v118, v118
	v_cndmask_b32_e32 v116, v159, v235, vcc
	v_cmp_gt_i32_e32 vcc, 0, v117
	v_mul_f32_e32 v116, v116, v119
	v_exp_f32_e32 v116, v116
	v_cndmask_b32_e32 v117, v159, v235, vcc
	v_mul_f32_e32 v117, v117, v118
	v_exp_f32_e32 v117, v117
	v_add_u32_e32 v118, -16, v242
	v_sub_u32_e32 v119, 16, v242
	v_max_i32_e32 v119, v118, v119
	v_pk_mul_f32 v[122:123], v[116:117], v[62:63]
	v_cmp_gt_i32_e32 vcc, 0, v118
	v_subrev_u32_e32 v117, 17, v242
	v_sub_u32_e32 v118, 17, v242
	v_max_i32_e32 v118, v117, v118
	v_cvt_f32_u32_e32 v119, v119
	v_cvt_f32_u32_e32 v118, v118
	v_cndmask_b32_e32 v116, v159, v235, vcc
	v_cmp_gt_i32_e32 vcc, 0, v117
	v_mul_f32_e32 v116, v116, v119
	v_exp_f32_e32 v116, v116
	v_cndmask_b32_e32 v117, v159, v235, vcc
	v_mul_f32_e32 v117, v117, v118
	v_exp_f32_e32 v117, v117
	v_subrev_u32_e32 v118, 18, v242
	v_sub_u32_e32 v119, 18, v242
	v_max_i32_e32 v119, v118, v119
	v_pk_mul_f32 v[180:181], v[116:117], v[104:105]
	v_cmp_gt_i32_e32 vcc, 0, v118
	v_subrev_u32_e32 v117, 19, v242
	v_sub_u32_e32 v118, 19, v242
	v_max_i32_e32 v118, v117, v118
	v_cvt_f32_u32_e32 v119, v119
	v_cvt_f32_u32_e32 v118, v118
	v_cndmask_b32_e32 v116, v159, v235, vcc
	v_cmp_gt_i32_e32 vcc, 0, v117
	v_mul_f32_e32 v116, v116, v119
	v_exp_f32_e32 v116, v116
	v_cndmask_b32_e32 v117, v159, v235, vcc
	v_mul_f32_e32 v117, v117, v118
	v_exp_f32_e32 v117, v117
	v_subrev_u32_e32 v118, 32, v242
	v_sub_u32_e32 v119, 32, v242
	v_max_i32_e32 v119, v118, v119
	v_pk_mul_f32 v[182:183], v[116:117], v[106:107]
	v_cmp_gt_i32_e32 vcc, 0, v118
	v_subrev_u32_e32 v117, 33, v242
	v_sub_u32_e32 v118, 33, v242
	v_max_i32_e32 v118, v117, v118
	v_cvt_f32_u32_e32 v119, v119
	v_cvt_f32_u32_e32 v118, v118
	v_cndmask_b32_e32 v116, v159, v235, vcc
	v_cmp_gt_i32_e32 vcc, 0, v117
	v_mul_f32_e32 v116, v116, v119
	v_sub_u32_e32 v119, 34, v242
	v_cndmask_b32_e32 v117, v159, v235, vcc
	v_mul_f32_e32 v117, v117, v118
	v_subrev_u32_e32 v118, 34, v242
	v_max_i32_e32 v119, v118, v119
	v_cvt_f32_u32_e32 v119, v119
	v_cmp_gt_i32_e32 vcc, 0, v118
	v_sub_u32_e32 v179, 48, v242
	v_sub_u32_e32 v243, 49, v242
	v_cndmask_b32_e32 v118, v159, v235, vcc
	v_mul_f32_e32 v118, v118, v119
	v_subrev_u32_e32 v119, 35, v242
	v_max_i32_e32 v178, v119, v178
	v_cvt_f32_u32_e32 v178, v178
	v_cmp_gt_i32_e32 vcc, 0, v119
	v_sub_u32_e32 v244, 50, v242
	v_exp_f32_e32 v116, v116
	v_cndmask_b32_e32 v119, v159, v235, vcc
	v_mul_f32_e32 v119, v119, v178
	v_subrev_u32_e32 v178, 48, v242
	v_max_i32_e32 v179, v178, v179
	v_cvt_f32_u32_e32 v179, v179
	v_cmp_gt_i32_e32 vcc, 0, v178
	v_exp_f32_e32 v117, v117
	v_exp_f32_e32 v118, v118
	v_cndmask_b32_e32 v178, v159, v235, vcc
	v_mul_f32_e32 v178, v178, v179
	v_subrev_u32_e32 v179, 49, v242
	v_max_i32_e32 v243, v179, v243
	v_cvt_f32_u32_e32 v243, v243
	v_cmp_gt_i32_e32 vcc, 0, v179
	v_exp_f32_e32 v119, v119
	v_exp_f32_e32 v178, v178
	v_cndmask_b32_e32 v179, v159, v235, vcc
	v_mul_f32_e32 v179, v179, v243
	v_subrev_u32_e32 v243, 50, v242
	v_max_i32_e32 v244, v243, v244
	v_cvt_f32_u32_e32 v244, v244
	v_cmp_gt_i32_e32 vcc, 0, v243
	v_exp_f32_e32 v179, v179
	v_pk_mul_f32 v[116:117], v[116:117], v[108:109]
	v_cndmask_b32_e32 v243, v159, v235, vcc
	v_mul_f32_e32 v243, v243, v244
	v_subrev_u32_e32 v244, 51, v242
	v_sub_u32_e32 v242, 51, v242
	v_max_i32_e32 v242, v244, v242
	v_cvt_f32_u32_e32 v242, v242
	v_cmp_gt_i32_e32 vcc, 0, v244
	v_exp_f32_e32 v245, v243
	v_pk_mul_f32 v[118:119], v[118:119], v[110:111]
	v_cndmask_b32_e32 v243, v159, v235, vcc
	v_mul_f32_e32 v242, v243, v242
	v_exp_f32_e32 v243, v242
	v_pk_mul_f32 v[178:179], v[178:179], v[56:57]
	v_mul_f32_e32 v242, v245, v58
	s_mov_b64 s[10:11], 0
